# attention: two barriers per tile (mid barrier after 16 of 32 exps), waves 4-7 one barrier behind, role-dependent K/V DMA issue, counted vmcnt; DMA address diet
# baseline (speedup 1.0000x reference)
.LBB0_185:
	s_waitcnt vmcnt(4)
	s_barrier
	v_mbcnt_lo_u32_b32 v192, -1, 0
	v_mbcnt_hi_u32_b32 v192, -1, v192
	s_cmp_lt_u32 s19, 4
	s_cbranch_scc0 .Ls0b1_lag
	s_add_u32 s98, s8, s14
	s_addc_u32 s99, s9, s15
	s_add_u32 s100, s8, s28
	s_addc_u32 s101, s9, s29
	s_add_i32 s36, s61, 0x10000
	s_mov_b32 m0, s36
	s_add_i32 s37, s36, 0x4000
	global_load_lds_dwordx4 v251, s[98:99]
	s_mov_b32 m0, s37
	s_add_i32 s36, s65, 0x10000
	global_load_lds_dwordx4 v251, s[100:101]
	s_mov_b32 m0, s36
	s_add_i32 s37, s36, 0x4000
	global_load_lds_dwordx4 v252, s[98:99]
	s_mov_b32 m0, s37
	s_nop 0
	global_load_lds_dwordx4 v252, s[100:101]
	s_branch .Ls0b1_done

.LBB0_188:
	v_mul_f32_e32 v191, 0xbe0293ee, v186
	v_fmamk_f32 v18, v18, 0x3e0293ee, v191
	v_fmamk_f32 v19, v19, 0x3e0293ee, v191
	v_exp_f32_e32 v18, v18
	v_fmamk_f32 v20, v20, 0x3e0293ee, v191
	v_exp_f32_e32 v19, v19
	v_fmamk_f32 v21, v21, 0x3e0293ee, v191
	v_exp_f32_e32 v20, v20
	v_fmamk_f32 v22, v22, 0x3e0293ee, v191
	v_fmamk_f32 v10, v10, 0x3e0293ee, v191
	v_exp_f32_e32 v21, v21
	v_fmamk_f32 v23, v23, 0x3e0293ee, v191
	v_exp_f32_e32 v22, v22
	v_exp_f32_e32 v194, v10
	v_add_f32_e32 v10, 0, v18
	v_fmamk_f32 v24, v24, 0x3e0293ee, v191
	v_exp_f32_e32 v23, v23
	v_add_f32_e32 v10, v19, v10
	v_fmamk_f32 v25, v25, 0x3e0293ee, v191
	v_exp_f32_e32 v24, v24
	v_add_f32_e32 v10, v20, v10
	v_fmamk_f32 v26, v26, 0x3e0293ee, v191
	v_exp_f32_e32 v25, v25
	v_add_f32_e32 v10, v21, v10
	v_fmamk_f32 v27, v27, 0x3e0293ee, v191
	v_exp_f32_e32 v26, v26
	v_add_f32_e32 v10, v22, v10
	v_fmamk_f32 v28, v28, 0x3e0293ee, v191
	v_exp_f32_e32 v27, v27
	v_add_f32_e32 v10, v23, v10
	v_fmamk_f32 v29, v29, 0x3e0293ee, v191
	v_exp_f32_e32 v28, v28
	v_add_f32_e32 v10, v24, v10
	v_fmamk_f32 v30, v30, 0x3e0293ee, v191
	v_exp_f32_e32 v29, v29
	v_add_f32_e32 v10, v25, v10
	v_fmamk_f32 v31, v31, 0x3e0293ee, v191
	v_exp_f32_e32 v30, v30
	v_add_f32_e32 v10, v26, v10
	v_fmamk_f32 v32, v32, 0x3e0293ee, v191
	v_exp_f32_e32 v31, v31
	v_add_f32_e32 v10, v27, v10
	v_fmamk_f32 v33, v33, 0x3e0293ee, v191
	v_exp_f32_e32 v32, v32
	s_waitcnt vmcnt(4)
	s_barrier
	s_cmp_lt_u32 s19, 4
	s_cbranch_scc0 .Ls0b2_lag
	s_add_i32 s36, s68, s79
	s_add_i32 s90, s36, 64
	s_mul_hi_i32 s91, s90, 0xa000
	s_mul_i32 s90, s90, 0xa000
	s_add_u32 s90, s82, s90
	s_addc_u32 s91, s83, s91
	s_add_u32 s98, s90, 0x80
	s_addc_u32 s99, s91, 0
	s_add_i32 s94, s47, s70
	s_mov_b32 m0, s94
	s_add_i32 s95, s94, 0x400
	global_load_lds_dwordx4 v253, s[90:91]
	s_mov_b32 m0, s95
	s_add_i32 s96, s47, s74
	global_load_lds_dwordx4 v253, s[98:99]
	s_mov_b32 m0, s96
	s_add_i32 s97, s47, s77
	global_load_lds_dwordx4 v254, s[90:91]
	s_mov_b32 m0, s97
	s_nop 0
	global_load_lds_dwordx4 v254, s[98:99]
	s_branch .Ls0b2_done

.Ls0b2_done:
	v_add_f32_e32 v10, v28, v10
	v_fmamk_f32 v2, v2, 0x3e0293ee, v191
	v_exp_f32_e32 v33, v33
	v_add_f32_e32 v10, v29, v10
	v_fmamk_f32 v3, v3, 0x3e0293ee, v191
	v_exp_f32_e32 v2, v2
	v_add_f32_e32 v10, v30, v10
	v_fmamk_f32 v4, v4, 0x3e0293ee, v191
	v_exp_f32_e32 v3, v3
	v_add_f32_e32 v10, v31, v10
	v_fmamk_f32 v5, v5, 0x3e0293ee, v191
	v_exp_f32_e32 v4, v4
	v_add_f32_e32 v10, v32, v10
	v_fmamk_f32 v6, v6, 0x3e0293ee, v191
	v_exp_f32_e32 v5, v5
	v_add_f32_e32 v10, v33, v10
	v_fmamk_f32 v7, v7, 0x3e0293ee, v191
	v_exp_f32_e32 v6, v6
	v_add_f32_e32 v10, v2, v10
	v_fmamk_f32 v8, v8, 0x3e0293ee, v191
	v_exp_f32_e32 v7, v7
	v_add_f32_e32 v10, v3, v10
	v_fmamk_f32 v9, v9, 0x3e0293ee, v191
	v_exp_f32_e32 v8, v8
	v_add_f32_e32 v10, v4, v10
	v_exp_f32_e32 v9, v9
	v_add_f32_e32 v10, v5, v10
	v_fmamk_f32 v11, v11, 0x3e0293ee, v191
	v_add_f32_e32 v10, v6, v10
	v_fmamk_f32 v12, v12, 0x3e0293ee, v191
	v_exp_f32_e32 v195, v11
	v_add_f32_e32 v10, v7, v10
	v_fmamk_f32 v13, v13, 0x3e0293ee, v191
	v_exp_f32_e32 v196, v12
	v_add_f32_e32 v10, v8, v10
	v_fmamk_f32 v14, v14, 0x3e0293ee, v191
	v_exp_f32_e32 v197, v13
	v_add_f32_e32 v10, v9, v10
	v_fmamk_f32 v15, v15, 0x3e0293ee, v191
	v_exp_f32_e32 v198, v14
	v_add_f32_e32 v10, v194, v10
	v_fmamk_f32 v16, v16, 0x3e0293ee, v191
	v_exp_f32_e32 v199, v15
	v_add_f32_e32 v10, v195, v10
	v_fmamk_f32 v17, v17, 0x3e0293ee, v191
	v_exp_f32_e32 v200, v16
	v_add_f32_e32 v10, v196, v10
	v_exp_f32_e32 v201, v17
	v_add_f32_e32 v10, v197, v10
	v_add_f32_e32 v10, v198, v10
	v_add_f32_e32 v10, v199, v10
	v_add_f32_e32 v10, v200, v10
	v_add_f32_e32 v189, v201, v10
	v_mov_b32_e32 v190, v189
	v_cvt_pk_bf16_f32 v10, v18, v19
	v_cvt_pk_bf16_f32 v11, v20, v21
	v_cvt_pk_bf16_f32 v12, v22, v23
	v_cvt_pk_bf16_f32 v13, v24, v25
	v_cvt_pk_bf16_f32 v14, v26, v27
	v_cvt_pk_bf16_f32 v15, v28, v29
	v_cvt_pk_bf16_f32 v16, v30, v31
	v_cvt_pk_bf16_f32 v17, v32, v33
	v_cvt_pk_bf16_f32 v2, v2, v3
	v_cvt_pk_bf16_f32 v3, v4, v5
	v_cvt_pk_bf16_f32 v4, v6, v7
	v_cvt_pk_bf16_f32 v5, v8, v9
	v_cvt_pk_bf16_f32 v6, v194, v195
	v_cvt_pk_bf16_f32 v7, v196, v197
	v_cvt_pk_bf16_f32 v8, v198, v199
	v_cvt_pk_bf16_f32 v9, v200, v201
	s_nop 1
	v_permlane32_swap_b32_e32 v189, v190
	v_permlane32_swap_b32_e32 v10, v12
	v_permlane32_swap_b32_e32 v11, v13
	v_permlane32_swap_b32_e32 v14, v16
	v_permlane32_swap_b32_e32 v15, v17
	v_permlane32_swap_b32_e32 v2, v4
	v_permlane32_swap_b32_e32 v3, v5
	v_permlane32_swap_b32_e32 v6, v8
	v_permlane32_swap_b32_e32 v7, v9
	v_cmp_gt_f32_e32 vcc, 1.0, v188
	s_cbranch_vccz .LBB0_192
	v_cmp_gt_u32_e32 vcc, 32, v192
	s_and_saveexec_b64 s[34:35], vcc
	v_lshl_add_u32 v18, v193, 2, s60
	ds_write_b32 v18, v188
	s_or_b64 exec, exec, s[34:35]
	v_mov_b32_e32 v18, v192
	s_waitcnt lgkmcnt(0)
	s_nop 0
	v_and_b32_e32 v18, -16, v18
	v_add_u32_e32 v22, s60, v18
	ds_read_b128 v[18:21], v22
	ds_read_b128 v[22:25], v22 offset:64
	s_waitcnt lgkmcnt(0)
	v_pk_mul_f32 v[60:61], v[60:61], v[20:21]
	v_pk_mul_f32 v[58:59], v[58:59], v[18:19]
	v_pk_mul_f32 v[64:65], v[64:65], v[20:21]
	v_pk_mul_f32 v[62:63], v[62:63], v[18:19]
	v_pk_mul_f32 v[68:69], v[68:69], v[20:21]
	v_pk_mul_f32 v[66:67], v[66:67], v[18:19]
	v_pk_mul_f32 v[72:73], v[72:73], v[20:21]
	v_pk_mul_f32 v[70:71], v[70:71], v[18:19]
	v_pk_mul_f32 v[76:77], v[76:77], v[20:21]
	v_pk_mul_f32 v[74:75], v[74:75], v[18:19]
	v_pk_mul_f32 v[84:85], v[84:85], v[20:21]
	v_pk_mul_f32 v[82:83], v[82:83], v[18:19]
	v_pk_mul_f32 v[92:93], v[92:93], v[20:21]
	v_pk_mul_f32 v[90:91], v[90:91], v[18:19]
	v_pk_mul_f32 v[100:101], v[100:101], v[20:21]
	v_pk_mul_f32 v[98:99], v[98:99], v[18:19]
	v_pk_mul_f32 v[112:113], v[112:113], v[20:21]
	v_pk_mul_f32 v[110:111], v[110:111], v[18:19]
	v_pk_mul_f32 v[124:125], v[124:125], v[20:21]
	v_pk_mul_f32 v[122:123], v[122:123], v[18:19]
	v_pk_mul_f32 v[136:137], v[136:137], v[20:21]
	v_pk_mul_f32 v[134:135], v[134:135], v[18:19]
	v_pk_mul_f32 v[148:149], v[148:149], v[20:21]
	v_pk_mul_f32 v[146:147], v[146:147], v[18:19]
	v_pk_mul_f32 v[160:161], v[160:161], v[20:21]
	v_pk_mul_f32 v[158:159], v[158:159], v[18:19]
	v_pk_mul_f32 v[176:177], v[176:177], v[20:21]
	v_pk_mul_f32 v[174:175], v[174:175], v[18:19]
	v_pk_mul_f32 v[184:185], v[184:185], v[20:21]
	v_pk_mul_f32 v[182:183], v[182:183], v[18:19]
	v_pk_mul_f32 v[172:173], v[172:173], v[20:21]
	v_pk_mul_f32 v[170:171], v[170:171], v[18:19]
	v_pk_mul_f32 v[180:181], v[180:181], v[24:25]
	v_pk_mul_f32 v[178:179], v[178:179], v[22:23]
	v_pk_mul_f32 v[168:169], v[168:169], v[24:25]
	v_pk_mul_f32 v[166:167], v[166:167], v[22:23]
	v_pk_mul_f32 v[164:165], v[164:165], v[24:25]
	v_pk_mul_f32 v[162:163], v[162:163], v[22:23]
	v_pk_mul_f32 v[156:157], v[156:157], v[24:25]
	v_pk_mul_f32 v[154:155], v[154:155], v[22:23]
	v_pk_mul_f32 v[152:153], v[152:153], v[24:25]
	v_pk_mul_f32 v[150:151], v[150:151], v[22:23]
	v_pk_mul_f32 v[144:145], v[144:145], v[24:25]
	v_pk_mul_f32 v[142:143], v[142:143], v[22:23]
	v_pk_mul_f32 v[140:141], v[140:141], v[24:25]
	v_pk_mul_f32 v[138:139], v[138:139], v[22:23]
	v_pk_mul_f32 v[132:133], v[132:133], v[24:25]
	v_pk_mul_f32 v[130:131], v[130:131], v[22:23]
	v_pk_mul_f32 v[128:129], v[128:129], v[24:25]
	v_pk_mul_f32 v[126:127], v[126:127], v[22:23]
	v_pk_mul_f32 v[120:121], v[120:121], v[24:25]
	v_pk_mul_f32 v[118:119], v[118:119], v[22:23]
	v_pk_mul_f32 v[116:117], v[116:117], v[24:25]
	v_pk_mul_f32 v[114:115], v[114:115], v[22:23]
	v_pk_mul_f32 v[108:109], v[108:109], v[24:25]
	v_pk_mul_f32 v[106:107], v[106:107], v[22:23]
	v_pk_mul_f32 v[104:105], v[104:105], v[24:25]
	v_pk_mul_f32 v[102:103], v[102:103], v[22:23]
	v_pk_mul_f32 v[96:97], v[96:97], v[24:25]
	v_pk_mul_f32 v[94:95], v[94:95], v[22:23]
	v_pk_mul_f32 v[88:89], v[88:89], v[24:25]
	v_pk_mul_f32 v[86:87], v[86:87], v[22:23]
	v_pk_mul_f32 v[80:81], v[80:81], v[24:25]
	v_pk_mul_f32 v[78:79], v[78:79], v[22:23]

.Ls1w_done:
	s_barrier
	s_cselect_b64 s[34:35], -1, 0
	s_and_b64 vcc, exec, s[34:35]
	v_mbcnt_lo_u32_b32 v192, -1, 0
	v_mbcnt_hi_u32_b32 v192, -1, v192
	s_cbranch_vccnz .LBB0_194
	s_cmp_lt_u32 s19, 4
	s_cbranch_scc0 .Ls1b1_lag
	s_add_u32 s98, s8, s30
	s_addc_u32 s99, s9, s31
	s_mov_b32 m0, s62
	s_nop 0
	global_load_lds_dwordx4 v251, s[98:99]
	s_mov_b32 m0, s63
	s_nop 0
	global_load_lds_dwordx4 v251, s[8:9]
	s_mov_b32 m0, s66
	s_nop 0
	global_load_lds_dwordx4 v252, s[98:99]
	s_mov_b32 m0, s67
	s_nop 0
	global_load_lds_dwordx4 v252, s[8:9]
	s_branch .LBB0_194

.LBB0_197:
	v_fmamk_f32 v18, v18, 0x3e0293ee, v191
	v_fmamk_f32 v19, v19, 0x3e0293ee, v191
	v_fmamk_f32 v20, v20, 0x3e0293ee, v191
	v_fmamk_f32 v21, v21, 0x3e0293ee, v191
	v_fmamk_f32 v22, v22, 0x3e0293ee, v191
	v_fmamk_f32 v23, v23, 0x3e0293ee, v191
	v_fmamk_f32 v24, v24, 0x3e0293ee, v191
	v_fmamk_f32 v25, v25, 0x3e0293ee, v191
	v_fmamk_f32 v26, v26, 0x3e0293ee, v191
	v_fmamk_f32 v27, v27, 0x3e0293ee, v191
	v_fmamk_f32 v28, v28, 0x3e0293ee, v191
	v_fmamk_f32 v29, v29, 0x3e0293ee, v191
	v_fmamk_f32 v30, v30, 0x3e0293ee, v191
	v_fmamk_f32 v31, v31, 0x3e0293ee, v191
	v_fmamk_f32 v32, v32, 0x3e0293ee, v191
	v_fmamk_f32 v33, v33, 0x3e0293ee, v191
	v_fmamk_f32 v2, v2, 0x3e0293ee, v191
	v_fmamk_f32 v3, v3, 0x3e0293ee, v191
	v_fmamk_f32 v4, v4, 0x3e0293ee, v191
	v_fmamk_f32 v5, v5, 0x3e0293ee, v191
	v_fmamk_f32 v6, v6, 0x3e0293ee, v191
	v_fmamk_f32 v7, v7, 0x3e0293ee, v191
	v_fmamk_f32 v8, v8, 0x3e0293ee, v191
	v_fmamk_f32 v9, v9, 0x3e0293ee, v191
	v_fmamk_f32 v10, v10, 0x3e0293ee, v191
	v_fmamk_f32 v11, v11, 0x3e0293ee, v191
	v_fmamk_f32 v12, v12, 0x3e0293ee, v191
	v_fmamk_f32 v13, v13, 0x3e0293ee, v191
	v_fmamk_f32 v14, v14, 0x3e0293ee, v191
	v_fmamk_f32 v15, v15, 0x3e0293ee, v191
	v_fmamk_f32 v16, v16, 0x3e0293ee, v191
	v_fmac_f32_e32 v191, 0x3e0293ee, v17
	v_exp_f32_e32 v17, v18
	v_exp_f32_e32 v195, v19
	v_exp_f32_e32 v20, v20
	v_exp_f32_e32 v21, v21
	v_exp_f32_e32 v22, v22
	v_exp_f32_e32 v196, v10
	v_add_f32_e32 v10, 0, v17
	v_exp_f32_e32 v23, v23
	v_add_f32_e32 v10, v195, v10
	v_exp_f32_e32 v24, v24
	v_add_f32_e32 v10, v20, v10
	v_exp_f32_e32 v25, v25
	v_add_f32_e32 v10, v21, v10
	v_exp_f32_e32 v26, v26
	v_add_f32_e32 v10, v22, v10
	v_exp_f32_e32 v27, v27
	v_add_f32_e32 v10, v23, v10
	v_exp_f32_e32 v28, v28
	v_add_f32_e32 v10, v24, v10
	v_exp_f32_e32 v29, v29
	v_add_f32_e32 v10, v25, v10
	v_exp_f32_e32 v30, v30
	v_add_f32_e32 v10, v26, v10
	v_exp_f32_e32 v31, v31
	v_add_f32_e32 v10, v27, v10
	v_exp_f32_e32 v32, v32
	s_cmp_ge_u32 s89, s80
	s_cbranch_scc1 .Ls1b2_nomore
	s_waitcnt vmcnt(4)
	s_barrier
	s_cmp_lt_u32 s19, 4
	s_cbranch_scc0 .Ls1b2_lag
	s_add_i32 s36, s68, s79
	s_addk_i32 s36, 0x80
	s_mul_hi_i32 s37, s36, 0xa000
	s_mul_i32 s36, s36, 0xa000
	s_add_u32 s36, s82, s36
	s_addc_u32 s37, s83, s37
	s_add_u32 s98, s36, 0x80
	s_addc_u32 s99, s37, 0
	s_mov_b32 m0, s71
	s_nop 0
	global_load_lds_dwordx4 v253, s[36:37]
	s_mov_b32 m0, s72
	s_nop 0
	global_load_lds_dwordx4 v253, s[98:99]
	s_mov_b32 m0, s75
	s_nop 0
	global_load_lds_dwordx4 v254, s[36:37]
	s_mov_b32 m0, s78
	s_nop 0
	global_load_lds_dwordx4 v254, s[98:99]
	s_branch .Ls1b2_done

.Ls1b2_done:
	v_add_f32_e32 v10, v28, v10
	v_exp_f32_e32 v33, v33
	v_add_f32_e32 v10, v29, v10
	v_exp_f32_e32 v2, v2
	v_add_f32_e32 v10, v30, v10
	v_exp_f32_e32 v3, v3
	v_add_f32_e32 v10, v31, v10
	v_exp_f32_e32 v4, v4
	v_add_f32_e32 v10, v32, v10
	v_exp_f32_e32 v5, v5
	v_add_f32_e32 v10, v33, v10
	v_exp_f32_e32 v6, v6
	v_add_f32_e32 v10, v2, v10
	v_exp_f32_e32 v7, v7
	v_add_f32_e32 v10, v3, v10
	v_exp_f32_e32 v8, v8
	v_add_f32_e32 v10, v4, v10
	v_exp_f32_e32 v9, v9
	v_add_f32_e32 v10, v5, v10
	v_add_f32_e32 v10, v6, v10
	v_exp_f32_e32 v197, v11
	v_add_f32_e32 v10, v7, v10
	v_exp_f32_e32 v198, v12
	v_add_f32_e32 v10, v8, v10
	v_exp_f32_e32 v199, v13
	v_add_f32_e32 v10, v9, v10
	v_exp_f32_e32 v200, v14
	v_add_f32_e32 v10, v196, v10
	v_exp_f32_e32 v201, v15
	v_add_f32_e32 v10, v197, v10
	v_exp_f32_e32 v202, v16
	v_add_f32_e32 v10, v198, v10
	v_exp_f32_e32 v191, v191
	v_add_f32_e32 v10, v199, v10
	v_add_f32_e32 v10, v200, v10
	v_add_f32_e32 v10, v201, v10
	v_add_f32_e32 v10, v202, v10
	v_add_f32_e32 v18, v191, v10
	v_mov_b32_e32 v19, v18
	v_cvt_pk_bf16_f32 v10, v17, v195
	v_cvt_pk_bf16_f32 v11, v20, v21
	v_cvt_pk_bf16_f32 v12, v22, v23
	v_cvt_pk_bf16_f32 v13, v24, v25
	v_cvt_pk_bf16_f32 v14, v26, v27
	v_cvt_pk_bf16_f32 v15, v28, v29
	v_cvt_pk_bf16_f32 v16, v30, v31
	v_cvt_pk_bf16_f32 v17, v32, v33
	v_cvt_pk_bf16_f32 v2, v2, v3
	v_cvt_pk_bf16_f32 v3, v4, v5
	v_cvt_pk_bf16_f32 v4, v6, v7
	v_cvt_pk_bf16_f32 v5, v8, v9
	v_cvt_pk_bf16_f32 v6, v196, v197
	v_cvt_pk_bf16_f32 v7, v198, v199
	v_cvt_pk_bf16_f32 v8, v200, v201
	v_cvt_pk_bf16_f32 v9, v202, v191
	s_nop 1
	v_permlane32_swap_b32_e32 v18, v19
	v_permlane32_swap_b32_e32 v10, v12
	v_permlane32_swap_b32_e32 v11, v13
	v_permlane32_swap_b32_e32 v14, v16
	v_permlane32_swap_b32_e32 v15, v17
	v_permlane32_swap_b32_e32 v2, v4
	v_permlane32_swap_b32_e32 v3, v5
	v_permlane32_swap_b32_e32 v6, v8
	v_permlane32_swap_b32_e32 v7, v9
	v_cmp_gt_f32_e32 vcc, 1.0, v193
	s_cbranch_vccz .LBB0_184
	v_cmp_gt_u32_e32 vcc, 32, v192
	s_and_saveexec_b64 s[36:37], vcc
	s_cbranch_execz .LBB0_183
	v_lshl_add_u32 v20, v194, 2, s60
	ds_write_b32 v20, v193
	s_branch .LBB0_183
